# attention: s_setprio 1 over each wave's PV+QK MFMA blocks, 0 over its softmax block
# baseline (speedup 1.0000x reference)
; #define LAS __attribute__((address_space(3)))
; DI void u_attn2(Frame& F, int h, int qb, int sp, int ntile) {
;     ...
;     for (int t = 0; t < ntile; ++t) {
;         const int kt = kt0 + t;
;         __syncthreads();
; #pragma unroll
;         for (int i = 0; i < 3; ++i) { const int p = tid + 512 * i, r = p / 24, cc = p - r * 24; *(LAS u32x4*)(Ks + r * 200 + cc * 8) = kreg[i]; }
; #pragma unroll
;         for (int i = 0; i < 2; ++i) { const int p = tid + 512 * i, r = p >> 3, cc = p & 7; *(LAS u32x4*)(Vs + r * 72 + cc * 8) = vreg[i]; }
;         __syncthreads();
;         if (t + 1 < ntile) AT_LOAD(kt + 1)
.LBB0_2236:
	s_setprio 0
	s_add_i32 s38, s46, 2
	s_cmp_lt_i32 s38, s45
	s_cbranch_scc0 .Latt_w0
	s_waitcnt vmcnt(6)
	s_branch .Latt_w1

; #define MFMA16(a, b, c) __builtin_amdgcn_mfma_f32_16x16x32_bf16((a), (b), (c), 0, 0, 0)
; #define AT_VLD(dst, db_) { _Pragma("unroll") for (int s2 = 0; s2 < 2; ++s2) { const LAS bf16* vp = Vs + ((db_) * 16 + lc) * 72 + 32 * s2 + 4 * g4; \
;                     const u32x2 v0 = *(const LAS u32x2*)vp, v1 = *(const LAS u32x2*)(vp + 16); const u32x4 vw = (u32x4){v0.x, v0.y, v1.x, v1.y}; dst[s2] = __builtin_bit_cast(bf16x8, vw); } }
; DI void u_attn2(Frame& F, int h, int qb, int sp, int ntile) {
;     ...
;             {
;                 bf16x8 vfr[2][2];
;     ...
;                 AT_VLD(vfr[0], 0)
; #pragma unroll
;                 for (int db = 0; db < 8; ++db) {
;                     if (db < 7) AT_VLD(vfr[(db + 1) & 1], db + 1)
; #pragma unroll
;                     for (int s2 = 0; s2 < 2; ++s2)
; #pragma unroll
;                         for (int qq = 0; qq < 2; ++qq) o[db][qq] = MFMA16(vfr[db & 1][s2], pf[qq][s2], o[db][qq]);
;                 }
.Latt_noload_A:
	s_setprio 1
	s_cmp_eq_u32 s46, 0
	s_cbranch_scc1 .Latt_A_qk
	v_add3_u32 v18, s46, v181, -1
	v_cmp_le_i32_e32 vcc, v18, v180
	s_cbranch_vccz .Latt_A_qk
	ds_read_b128 v[146:149], v110 offset:26624
	ds_read_b128 v[244:247], v110 offset:26688
	ds_read_b128 v[220:223], v110 offset:29184
	ds_read_b128 v[224:227], v110 offset:29248
	s_waitcnt lgkmcnt(3)
	v_mfma_f32_16x16x32_bf16 v[134:137], v[146:149], v[198:201], v[134:137]
	v_mfma_f32_16x16x32_bf16 v[118:121], v[146:149], v[210:213], v[118:121]
	ds_read_b128 v[146:149], v110 offset:31744
	s_waitcnt lgkmcnt(3)
	v_mfma_f32_16x16x32_bf16 v[134:137], v[244:247], v[192:195], v[134:137]
	v_mfma_f32_16x16x32_bf16 v[118:121], v[244:247], v[142:145], v[118:121]
	ds_read_b128 v[244:247], v110 offset:31808
	s_waitcnt lgkmcnt(3)
	v_mfma_f32_16x16x32_bf16 v[106:109], v[220:223], v[198:201], v[106:109]
	v_mfma_f32_16x16x32_bf16 v[102:105], v[220:223], v[210:213], v[102:105]
	ds_read_b128 v[220:223], v110 offset:34304
	s_waitcnt lgkmcnt(3)
	v_mfma_f32_16x16x32_bf16 v[106:109], v[224:227], v[192:195], v[106:109]
	v_mfma_f32_16x16x32_bf16 v[102:105], v[224:227], v[142:145], v[102:105]
	ds_read_b128 v[224:227], v110 offset:34368
	s_waitcnt lgkmcnt(3)
	v_mfma_f32_16x16x32_bf16 v[98:101], v[146:149], v[198:201], v[98:101]
	v_mfma_f32_16x16x32_bf16 v[94:97], v[146:149], v[210:213], v[94:97]
	ds_read_b128 v[146:149], v110 offset:36864
	s_waitcnt lgkmcnt(3)
	v_mfma_f32_16x16x32_bf16 v[98:101], v[244:247], v[192:195], v[98:101]
	v_mfma_f32_16x16x32_bf16 v[94:97], v[244:247], v[142:145], v[94:97]
	ds_read_b128 v[244:247], v110 offset:36928
	s_waitcnt lgkmcnt(3)
	v_mfma_f32_16x16x32_bf16 v[90:93], v[220:223], v[198:201], v[90:93]
	v_mfma_f32_16x16x32_bf16 v[86:89], v[220:223], v[210:213], v[86:89]
	ds_read_b128 v[220:223], v110 offset:39424
	s_waitcnt lgkmcnt(3)
	v_mfma_f32_16x16x32_bf16 v[90:93], v[224:227], v[192:195], v[90:93]
	v_mfma_f32_16x16x32_bf16 v[86:89], v[224:227], v[142:145], v[86:89]
	ds_read_b128 v[224:227], v110 offset:39488
	s_waitcnt lgkmcnt(3)
	v_mfma_f32_16x16x32_bf16 v[82:85], v[146:149], v[198:201], v[82:85]
	v_mfma_f32_16x16x32_bf16 v[78:81], v[146:149], v[210:213], v[78:81]
	ds_read_b128 v[146:149], v110 offset:41984
	s_waitcnt lgkmcnt(3)
	v_mfma_f32_16x16x32_bf16 v[82:85], v[244:247], v[192:195], v[82:85]
	v_mfma_f32_16x16x32_bf16 v[78:81], v[244:247], v[142:145], v[78:81]
	ds_read_b128 v[244:247], v110 offset:42048
	s_waitcnt lgkmcnt(3)
	v_mfma_f32_16x16x32_bf16 v[70:73], v[220:223], v[198:201], v[70:73]
	v_mfma_f32_16x16x32_bf16 v[74:77], v[220:223], v[210:213], v[74:77]
	ds_read_b128 v[220:223], v110 offset:44544
	s_waitcnt lgkmcnt(3)
	v_mfma_f32_16x16x32_bf16 v[70:73], v[224:227], v[192:195], v[70:73]
	v_mfma_f32_16x16x32_bf16 v[74:77], v[224:227], v[142:145], v[74:77]
	ds_read_b128 v[224:227], v110 offset:44608
	s_waitcnt lgkmcnt(3)
	v_mfma_f32_16x16x32_bf16 v[66:69], v[146:149], v[198:201], v[66:69]
	v_mfma_f32_16x16x32_bf16 v[58:61], v[146:149], v[210:213], v[58:61]
	s_waitcnt lgkmcnt(2)
	v_mfma_f32_16x16x32_bf16 v[66:69], v[244:247], v[192:195], v[66:69]
	v_mfma_f32_16x16x32_bf16 v[58:61], v[244:247], v[142:145], v[58:61]
	s_waitcnt lgkmcnt(1)
	v_mfma_f32_16x16x32_bf16 v[54:57], v[220:223], v[198:201], v[54:57]
	v_mfma_f32_16x16x32_bf16 v[62:65], v[220:223], v[210:213], v[62:65]
	s_waitcnt lgkmcnt(0)
	v_mfma_f32_16x16x32_bf16 v[54:57], v[224:227], v[192:195], v[54:57]
	v_mfma_f32_16x16x32_bf16 v[62:65], v[224:227], v[142:145], v[62:65]
; DI float xr16_max(float x) { float a = x, b = x; XR_SWAP("v_permlane16_swap_b32", a, b); return fmaxf(a, b); }
; DI float xr32_max(float x) { float a = x, b = x; XR_SWAP("v_permlane32_swap_b32", a, b); return fmaxf(a, b); }
; #define MFMA16(a, b, c) __builtin_amdgcn_mfma_f32_16x16x32_bf16((a), (b), (c), 0, 0, 0)
; DI void u_attn2(Frame& F, int h, int qb, int sp, int ntile) {
;     ...
;         if (kt <= cw) {
;             f32x4 s[4][2];
; #pragma unroll
;             for (int kb = 0; kb < 4; ++kb)
; #pragma unroll
;                 for (int qq = 0; qq < 2; ++qq) s[kb][qq] = (f32x4){0.f, 0.f, 0.f, 0.f};
;             {
;                 bf16x8 kfr[2][4];
; #pragma unroll
;                 for (int kb = 0; kb < 4; ++kb) kfr[0][kb] = ldfrag(Ks, 200, kb * 16, 0, lane);
; #pragma unroll
;                 for (int ks = 0; ks < 6; ++ks) {
;                     if (ks < 5) {
; #pragma unroll
;                         for (int kb = 0; kb < 4; ++kb) kfr[(ks + 1) & 1][kb] = ldfrag(Ks, 200, kb * 16, (ks + 1) * 32, lane); }
; #pragma unroll
;                     for (int kb = 0; kb < 4; ++kb)
; #pragma unroll
;                         for (int qq = 0; qq < 2; ++qq) s[kb][qq] = MFMA16(kfr[ks & 1][kb], qf[qq][ks], s[kb][qq]);
;                 }
;             }
;             bf16x8 pf[2][2];
; #pragma unroll
;             for (int qq = 0; qq < 2; ++qq) {
;                 float mx = -1e30f;
; #pragma unroll
;                 for (int kb = 0; kb < 4; ++kb) mx = fmaxf(mx, fmaxf(fmaxf(s[kb][qq][0], s[kb][qq][1]), fmaxf(s[kb][qq][2], s[kb][qq][3])));
;                 mx = xr32_max(xr16_max(mx));
.Latt_A_qk:
	v_cmp_lt_i32_e32 vcc, s46, v179
	s_cbranch_vccz .LBB0_2236
	v_add_u32_e32 v18, s46, v181
	v_cmp_le_i32_e32 vcc, v18, v180
	s_cbranch_vccz .LBB0_2236
	ds_read_b128 v[138:141], v112
	ds_read_b128 v[142:145], v112 offset:6656
	ds_read_b128 v[146:149], v112 offset:13312
	ds_read_b128 v[150:153], v112 offset:19968
	ds_read_b128 v[154:157], v112 offset:64
	ds_read_b128 v[192:195], v112 offset:6720
	ds_read_b128 v[210:213], v112 offset:13376
	ds_read_b128 v[214:217], v112 offset:20032
	s_waitcnt lgkmcnt(7)
	v_mfma_f32_16x16x32_bf16 v[218:221], v[138:141], v[2:5], v[114:117]
	ds_read_b128 v[244:247], v112 offset:128
	ds_read_b128 v[248:251], v112 offset:6784
	ds_read_b128 v[198:201], v112 offset:13440
	ds_read_b128 v[230:233], v112 offset:20096
	v_mov_b32_e32 v234, 0x42800000
	v_mfma_f32_16x16x32_bf16 v[138:141], v[138:141], v[30:33], v[128:131]
	s_waitcnt lgkmcnt(10)
	v_mfma_f32_16x16x32_bf16 v[222:225], v[142:145], v[2:5], v[114:117]
	v_mfma_f32_16x16x32_bf16 v[142:145], v[142:145], v[30:33], v[128:131]
	s_waitcnt lgkmcnt(9)
	v_mfma_f32_16x16x32_bf16 v[226:229], v[146:149], v[2:5], v[114:117]
	s_waitcnt lgkmcnt(7)
	v_mfma_f32_16x16x32_bf16 v[218:221], v[154:157], v[6:9], v[218:221]
	v_mfma_f32_16x16x32_bf16 v[146:149], v[146:149], v[30:33], v[128:131]
	v_mfma_f32_16x16x32_bf16 v[240:243], v[150:153], v[2:5], v[114:117]
	v_mfma_f32_16x16x32_bf16 v[150:153], v[150:153], v[30:33], v[128:131]
	v_mfma_f32_16x16x32_bf16 v[138:141], v[154:157], v[34:37], v[138:141]
	s_waitcnt lgkmcnt(6)
	v_mfma_f32_16x16x32_bf16 v[154:157], v[192:195], v[6:9], v[222:225]
	v_mfma_f32_16x16x32_bf16 v[142:145], v[192:195], v[34:37], v[142:145]
	s_waitcnt lgkmcnt(5)
	v_mfma_f32_16x16x32_bf16 v[192:195], v[210:213], v[6:9], v[226:229]
	s_waitcnt lgkmcnt(3)
	v_mfma_f32_16x16x32_bf16 v[218:221], v[244:247], v[10:13], v[218:221]
	v_mfma_f32_16x16x32_bf16 v[146:149], v[210:213], v[34:37], v[146:149]
	v_mfma_f32_16x16x32_bf16 v[210:213], v[214:217], v[6:9], v[240:243]
	v_mfma_f32_16x16x32_bf16 v[150:153], v[214:217], v[34:37], v[150:153]
	ds_read_b128 v[214:217], v112 offset:192
	ds_read_b128 v[222:225], v112 offset:6848
	ds_read_b128 v[226:229], v112 offset:13504
	ds_read_b128 v[240:243], v112 offset:20160
	v_mfma_f32_16x16x32_bf16 v[138:141], v[244:247], v[38:41], v[138:141]
	s_waitcnt lgkmcnt(6)
	v_mfma_f32_16x16x32_bf16 v[154:157], v[248:251], v[10:13], v[154:157]
	v_mfma_f32_16x16x32_bf16 v[142:145], v[248:251], v[38:41], v[142:145]
	s_waitcnt lgkmcnt(5)
	v_mfma_f32_16x16x32_bf16 v[192:195], v[198:201], v[10:13], v[192:195]
	s_waitcnt lgkmcnt(3)
	v_mfma_f32_16x16x32_bf16 v[218:221], v[214:217], v[14:17], v[218:221]
	v_mfma_f32_16x16x32_bf16 v[146:149], v[198:201], v[38:41], v[146:149]
	v_mfma_f32_16x16x32_bf16 v[198:201], v[230:233], v[10:13], v[210:213]
	v_mfma_f32_16x16x32_bf16 v[150:153], v[230:233], v[38:41], v[150:153]
	s_nop 1
	ds_read_b128 v[210:213], v112 offset:256
	ds_read_b128 v[230:233], v112 offset:6912
	ds_read_b128 v[244:247], v112 offset:13568
	ds_read_b128 v[248:251], v112 offset:20224
	v_mfma_f32_16x16x32_bf16 v[138:141], v[214:217], v[42:45], v[138:141]
	s_waitcnt lgkmcnt(6)
	v_mfma_f32_16x16x32_bf16 v[154:157], v[222:225], v[14:17], v[154:157]
	v_mfma_f32_16x16x32_bf16 v[142:145], v[222:225], v[42:45], v[142:145]
	s_waitcnt lgkmcnt(5)
	v_mfma_f32_16x16x32_bf16 v[192:195], v[226:229], v[14:17], v[192:195]
	s_waitcnt lgkmcnt(3)
	v_mfma_f32_16x16x32_bf16 v[218:221], v[210:213], v[22:25], v[218:221]
	v_mfma_f32_16x16x32_bf16 v[198:201], v[240:243], v[14:17], v[198:201]
	v_mfma_f32_16x16x32_bf16 v[150:153], v[240:243], v[42:45], v[150:153]
	v_mfma_f32_16x16x32_bf16 v[138:141], v[210:213], v[46:49], v[138:141]
	s_waitcnt lgkmcnt(2)
	v_mfma_f32_16x16x32_bf16 v[154:157], v[230:233], v[22:25], v[154:157]
	v_mfma_f32_16x16x32_bf16 v[146:149], v[226:229], v[42:45], v[146:149]
	ds_read_b128 v[214:217], v112 offset:320
	ds_read_b128 v[222:225], v112 offset:6976
	ds_read_b128 v[226:229], v112 offset:13632
	ds_read_b128 v[240:243], v112 offset:20288
	v_mfma_f32_16x16x32_bf16 v[142:145], v[230:233], v[46:49], v[142:145]
	s_waitcnt lgkmcnt(5)
	v_mfma_f32_16x16x32_bf16 v[192:195], v[244:247], v[22:25], v[192:195]
	s_waitcnt lgkmcnt(3)
	v_mfma_f32_16x16x32_bf16 v[218:221], v[214:217], v[26:29], v[218:221]
	v_mfma_f32_16x16x32_bf16 v[198:201], v[248:251], v[22:25], v[198:201]
	v_mfma_f32_16x16x32_bf16 v[230:233], v[248:251], v[46:49], v[150:153]
	v_mfma_f32_16x16x32_bf16 v[150:153], v[214:217], v[50:53], v[138:141]
	s_waitcnt lgkmcnt(2)
	v_mfma_f32_16x16x32_bf16 v[214:217], v[222:225], v[26:29], v[154:157]
	v_mfma_f32_16x16x32_bf16 v[210:213], v[244:247], v[46:49], v[146:149]
	v_mfma_f32_16x16x32_bf16 v[146:149], v[222:225], v[50:53], v[142:145]
	s_waitcnt lgkmcnt(1)
	v_mfma_f32_16x16x32_bf16 v[222:225], v[226:229], v[26:29], v[192:195]
	s_waitcnt lgkmcnt(0)
	v_mfma_f32_16x16x32_bf16 v[154:157], v[240:243], v[26:29], v[198:201]
	v_mfma_f32_16x16x32_bf16 v[138:141], v[240:243], v[50:53], v[230:233]
	s_nop 1
	v_mfma_f32_16x16x32_bf16 v[142:145], v[226:229], v[50:53], v[210:213]
	s_setprio 0
	s_nop 7
	s_nop 1
	v_max3_f32 v198, v218, v219, v220
	v_max3_f32 v210, v150, v151, v152
	v_max3_f32 v199, v221, v214, v215
	v_max3_f32 v211, v153, v146, v147
	v_max3_f32 v200, v216, v217, v222
	v_max3_f32 v212, v148, v149, v142
	v_max3_f32 v201, v223, v224, v225
	v_max3_f32 v213, v143, v144, v145
	v_max3_f32 v192, v154, v155, v156
	v_max3_f32 v193, v138, v139, v140
	v_max3_f32 v198, v198, v199, v157
	v_max3_f32 v210, v210, v211, v141
	v_max3_f32 v200, v200, v201, v192
	v_max3_f32 v212, v212, v213, v193
	v_max3_f32 v18, v198, v200, s1
	v_max3_f32 v20, v210, v212, s1
	s_cmp_eq_u32 s46, 0
	s_cbranch_scc1 .Latt_slow_A
	v_max_f32_e32 v198, v18, v20
	v_cmp_lt_f32_e32 vcc, 0x41000000, v198
	s_cbranch_vccz .Latt_r1_A
